# v55 + EpiMergeAcc epilogue software-pipelined (3-deep g/m loads, counted vmcnt)
# speedup vs baseline: 1.0049x; 1.0049x over previous
.LBB0_445:
	v_lshl_or_b32 v132, s40, 8, v174
	v_lshl_add_u32 v176, s41, 8, v172
	v_ashrrev_i32_e32 v133, 31, v132
	v_lshlrev_b64 v[166:167], 1, v[132:133]
	v_mad_i64_i32 v[132:133], s[0:1], s35, v176, 0
	v_lshl_add_u64 v[132:133], v[132:133], 1, s[42:43]
	v_lshl_add_u64 v[232:233], v[132:133], 0, v[166:167]
	v_readlane_b32 s0, v254, 58
	v_readlane_b32 s1, v254, 59
	s_movk_i32 s2, 0x3080
	s_lshl_b32 s10, s35, 5
	s_mov_b32 s11, 0
	v_mov_b64_e32 v[132:133], s[0:1]
	v_mad_i64_i32 v[132:133], s[0:1], v176, s2, v[132:133]
	v_lshl_add_u64 v[234:235], v[132:133], 0, v[166:167]
	v_mov_b64_e32 v[236:237], v[234:235]
	s_mul_i32 s2, s35, 0xa0
	s_mov_b32 s3, 0
	s_mov_b32 s44, 0x30800
	s_mov_b32 s45, 0
	s_mov_b32 s46, 0xf2800
	s_mov_b32 s47, 0
	s_mov_b32 s48, 0xffff0000
	s_and_b64 vcc, exec, s[6:7]
	s_cbranch_vccz .Lmrg_first
	global_load_dwordx4 v[200:203], v[232:233], off
	global_load_dwordx4 v[204:207], v[234:235], off offset:3072
	global_load_dwordx4 v[208:211], v[232:233], off offset:256
	global_load_dwordx4 v[212:215], v[234:235], off offset:3328
	v_lshl_add_u64 v[232:233], v[232:233], 0, s[10:11]
	v_lshl_add_u64 v[234:235], v[234:235], 0, s[44:45]
	global_load_dwordx4 v[216:219], v[232:233], off
	global_load_dwordx4 v[220:223], v[234:235], off offset:3072
	global_load_dwordx4 v[224:227], v[232:233], off offset:256
	global_load_dwordx4 v[228:231], v[234:235], off offset:3328
	s_waitcnt vmcnt(6)
	v_lshlrev_b32_e32 v238, 16, v200
	v_and_b32_e32 v239, s48, v200
	v_lshlrev_b32_e32 v240, 16, v204
	v_and_b32_e32 v204, s48, v204
	v_fmac_f32_e32 v240, v128, v238
	v_fmac_f32_e32 v204, v129, v239
	v_cvt_pk_bf16_f32 v200, v240, v204
	v_lshlrev_b32_e32 v238, 16, v201
	v_and_b32_e32 v239, s48, v201
	v_lshlrev_b32_e32 v240, 16, v205
	v_and_b32_e32 v205, s48, v205
	v_fmac_f32_e32 v240, v130, v238
	v_fmac_f32_e32 v205, v131, v239
	v_cvt_pk_bf16_f32 v201, v240, v205
	v_lshlrev_b32_e32 v238, 16, v202
	v_and_b32_e32 v239, s48, v202
	v_lshlrev_b32_e32 v240, 16, v206
	v_and_b32_e32 v206, s48, v206
	v_fmac_f32_e32 v240, v124, v238
	v_fmac_f32_e32 v206, v125, v239
	v_cvt_pk_bf16_f32 v202, v240, v206
	v_lshlrev_b32_e32 v238, 16, v203
	v_and_b32_e32 v239, s48, v203
	v_lshlrev_b32_e32 v240, 16, v207
	v_and_b32_e32 v207, s48, v207
	v_fmac_f32_e32 v240, v126, v238
	v_fmac_f32_e32 v207, v127, v239
	v_cvt_pk_bf16_f32 v203, v240, v207
	global_store_dwordx4 v[236:237], v[200:203], off offset:3072
	v_lshl_add_u64 v[232:233], v[232:233], 0, s[10:11]
	v_lshl_add_u64 v[234:235], v[234:235], 0, s[44:45]
	global_load_dwordx4 v[200:203], v[232:233], off
	global_load_dwordx4 v[204:207], v[234:235], off offset:3072
	s_waitcnt vmcnt(7)
	v_lshlrev_b32_e32 v238, 16, v208
	v_and_b32_e32 v239, s48, v208
	v_lshlrev_b32_e32 v240, 16, v212
	v_and_b32_e32 v212, s48, v212
	v_fmac_f32_e32 v240, v120, v238
	v_fmac_f32_e32 v212, v121, v239
	v_cvt_pk_bf16_f32 v208, v240, v212
	v_lshlrev_b32_e32 v238, 16, v209
	v_and_b32_e32 v239, s48, v209
	v_lshlrev_b32_e32 v240, 16, v213
	v_and_b32_e32 v213, s48, v213
	v_fmac_f32_e32 v240, v122, v238
	v_fmac_f32_e32 v213, v123, v239
	v_cvt_pk_bf16_f32 v209, v240, v213
	v_lshlrev_b32_e32 v238, 16, v210
	v_and_b32_e32 v239, s48, v210
	v_lshlrev_b32_e32 v240, 16, v214
	v_and_b32_e32 v214, s48, v214
	v_fmac_f32_e32 v240, v116, v238
	v_fmac_f32_e32 v214, v117, v239
	v_cvt_pk_bf16_f32 v210, v240, v214
	v_lshlrev_b32_e32 v238, 16, v211
	v_and_b32_e32 v239, s48, v211
	v_lshlrev_b32_e32 v240, 16, v215
	v_and_b32_e32 v215, s48, v215
	v_fmac_f32_e32 v240, v118, v238
	v_fmac_f32_e32 v215, v119, v239
	v_cvt_pk_bf16_f32 v211, v240, v215
	global_store_dwordx4 v[236:237], v[208:211], off offset:3328
	global_load_dwordx4 v[208:211], v[232:233], off offset:256
	global_load_dwordx4 v[212:215], v[234:235], off offset:3328
	s_waitcnt vmcnt(8)
	v_lshlrev_b32_e32 v238, 16, v216
	v_and_b32_e32 v239, s48, v216
	v_lshlrev_b32_e32 v240, 16, v220
	v_and_b32_e32 v220, s48, v220
	v_fmac_f32_e32 v240, v112, v238
	v_fmac_f32_e32 v220, v113, v239
	v_cvt_pk_bf16_f32 v216, v240, v220
	v_lshlrev_b32_e32 v238, 16, v217
	v_and_b32_e32 v239, s48, v217
	v_lshlrev_b32_e32 v240, 16, v221
	v_and_b32_e32 v221, s48, v221
	v_fmac_f32_e32 v240, v114, v238
	v_fmac_f32_e32 v221, v115, v239
	v_cvt_pk_bf16_f32 v217, v240, v221
	v_lshlrev_b32_e32 v238, 16, v218
	v_and_b32_e32 v239, s48, v218
	v_lshlrev_b32_e32 v240, 16, v222
	v_and_b32_e32 v222, s48, v222
	v_fmac_f32_e32 v240, v108, v238
	v_fmac_f32_e32 v222, v109, v239
	v_cvt_pk_bf16_f32 v218, v240, v222
	v_lshlrev_b32_e32 v238, 16, v219
	v_and_b32_e32 v239, s48, v219
	v_lshlrev_b32_e32 v240, 16, v223
	v_and_b32_e32 v223, s48, v223
	v_fmac_f32_e32 v240, v110, v238
	v_fmac_f32_e32 v223, v111, v239
	v_cvt_pk_bf16_f32 v219, v240, v223
	v_lshl_add_u64 v[236:237], v[236:237], 0, s[44:45]
	global_store_dwordx4 v[236:237], v[216:219], off offset:3072
	v_lshl_add_u64 v[232:233], v[232:233], 0, s[10:11]
	v_lshl_add_u64 v[234:235], v[234:235], 0, s[44:45]
	global_load_dwordx4 v[216:219], v[232:233], off
	global_load_dwordx4 v[220:223], v[234:235], off offset:3072
	s_waitcnt vmcnt(9)
	v_lshlrev_b32_e32 v238, 16, v224
	v_and_b32_e32 v239, s48, v224
	v_lshlrev_b32_e32 v240, 16, v228
	v_and_b32_e32 v228, s48, v228
	v_fmac_f32_e32 v240, v104, v238
	v_fmac_f32_e32 v228, v105, v239
	v_cvt_pk_bf16_f32 v224, v240, v228
	v_lshlrev_b32_e32 v238, 16, v225
	v_and_b32_e32 v239, s48, v225
	v_lshlrev_b32_e32 v240, 16, v229
	v_and_b32_e32 v229, s48, v229
	v_fmac_f32_e32 v240, v106, v238
	v_fmac_f32_e32 v229, v107, v239
	v_cvt_pk_bf16_f32 v225, v240, v229
	v_lshlrev_b32_e32 v238, 16, v226
	v_and_b32_e32 v239, s48, v226
	v_lshlrev_b32_e32 v240, 16, v230
	v_and_b32_e32 v230, s48, v230
	v_fmac_f32_e32 v240, v100, v238
	v_fmac_f32_e32 v230, v101, v239
	v_cvt_pk_bf16_f32 v226, v240, v230
	v_lshlrev_b32_e32 v238, 16, v227
	v_and_b32_e32 v239, s48, v227
	v_lshlrev_b32_e32 v240, 16, v231
	v_and_b32_e32 v231, s48, v231
	v_fmac_f32_e32 v240, v102, v238
	v_fmac_f32_e32 v231, v103, v239
	v_cvt_pk_bf16_f32 v227, v240, v231
	global_store_dwordx4 v[236:237], v[224:227], off offset:3328
	global_load_dwordx4 v[224:227], v[232:233], off offset:256
	global_load_dwordx4 v[228:231], v[234:235], off offset:3328
	s_waitcnt vmcnt(9)
	v_lshlrev_b32_e32 v238, 16, v200
	v_and_b32_e32 v239, s48, v200
	v_lshlrev_b32_e32 v240, 16, v204
	v_and_b32_e32 v204, s48, v204
	v_fmac_f32_e32 v240, v96, v238
	v_fmac_f32_e32 v204, v97, v239
	v_cvt_pk_bf16_f32 v200, v240, v204
	v_lshlrev_b32_e32 v238, 16, v201
	v_and_b32_e32 v239, s48, v201
	v_lshlrev_b32_e32 v240, 16, v205
	v_and_b32_e32 v205, s48, v205
	v_fmac_f32_e32 v240, v98, v238
	v_fmac_f32_e32 v205, v99, v239
	v_cvt_pk_bf16_f32 v201, v240, v205
	v_lshlrev_b32_e32 v238, 16, v202
	v_and_b32_e32 v239, s48, v202
	v_lshlrev_b32_e32 v240, 16, v206
	v_and_b32_e32 v206, s48, v206
	v_fmac_f32_e32 v240, v92, v238
	v_fmac_f32_e32 v206, v93, v239
	v_cvt_pk_bf16_f32 v202, v240, v206
	v_lshlrev_b32_e32 v238, 16, v203
	v_and_b32_e32 v239, s48, v203
	v_lshlrev_b32_e32 v240, 16, v207
	v_and_b32_e32 v207, s48, v207
	v_fmac_f32_e32 v240, v94, v238
	v_fmac_f32_e32 v207, v95, v239
	v_cvt_pk_bf16_f32 v203, v240, v207
	v_lshl_add_u64 v[236:237], v[236:237], 0, s[44:45]
	global_store_dwordx4 v[236:237], v[200:203], off offset:3072
	v_lshl_add_u64 v[232:233], v[232:233], 0, s[2:3]
	v_lshl_add_u64 v[234:235], v[234:235], 0, s[46:47]
	global_load_dwordx4 v[200:203], v[232:233], off
	global_load_dwordx4 v[204:207], v[234:235], off offset:3072
	s_waitcnt vmcnt(9)
	v_lshlrev_b32_e32 v238, 16, v208
	v_and_b32_e32 v239, s48, v208
	v_lshlrev_b32_e32 v240, 16, v212
	v_and_b32_e32 v212, s48, v212
	v_fmac_f32_e32 v240, v88, v238
	v_fmac_f32_e32 v212, v89, v239
	v_cvt_pk_bf16_f32 v208, v240, v212
	v_lshlrev_b32_e32 v238, 16, v209
	v_and_b32_e32 v239, s48, v209
	v_lshlrev_b32_e32 v240, 16, v213
	v_and_b32_e32 v213, s48, v213
	v_fmac_f32_e32 v240, v90, v238
	v_fmac_f32_e32 v213, v91, v239
	v_cvt_pk_bf16_f32 v209, v240, v213
	v_lshlrev_b32_e32 v238, 16, v210
	v_and_b32_e32 v239, s48, v210
	v_lshlrev_b32_e32 v240, 16, v214
	v_and_b32_e32 v214, s48, v214
	v_fmac_f32_e32 v240, v84, v238
	v_fmac_f32_e32 v214, v85, v239
	v_cvt_pk_bf16_f32 v210, v240, v214
	v_lshlrev_b32_e32 v238, 16, v211
	v_and_b32_e32 v239, s48, v211
	v_lshlrev_b32_e32 v240, 16, v215
	v_and_b32_e32 v215, s48, v215
	v_fmac_f32_e32 v240, v86, v238
	v_fmac_f32_e32 v215, v87, v239
	v_cvt_pk_bf16_f32 v211, v240, v215
	global_store_dwordx4 v[236:237], v[208:211], off offset:3328
	global_load_dwordx4 v[208:211], v[232:233], off offset:256
	global_load_dwordx4 v[212:215], v[234:235], off offset:3328
	s_waitcnt vmcnt(9)
	v_lshlrev_b32_e32 v238, 16, v216
	v_and_b32_e32 v239, s48, v216
	v_lshlrev_b32_e32 v240, 16, v220
	v_and_b32_e32 v220, s48, v220
	v_fmac_f32_e32 v240, v80, v238
	v_fmac_f32_e32 v220, v81, v239
	v_cvt_pk_bf16_f32 v216, v240, v220
	v_lshlrev_b32_e32 v238, 16, v217
	v_and_b32_e32 v239, s48, v217
	v_lshlrev_b32_e32 v240, 16, v221
	v_and_b32_e32 v221, s48, v221
	v_fmac_f32_e32 v240, v82, v238
	v_fmac_f32_e32 v221, v83, v239
	v_cvt_pk_bf16_f32 v217, v240, v221
	v_lshlrev_b32_e32 v238, 16, v218
	v_and_b32_e32 v239, s48, v218
	v_lshlrev_b32_e32 v240, 16, v222
	v_and_b32_e32 v222, s48, v222
	v_fmac_f32_e32 v240, v76, v238
	v_fmac_f32_e32 v222, v77, v239
	v_cvt_pk_bf16_f32 v218, v240, v222
	v_lshlrev_b32_e32 v238, 16, v219
	v_and_b32_e32 v239, s48, v219
	v_lshlrev_b32_e32 v240, 16, v223
	v_and_b32_e32 v223, s48, v223
	v_fmac_f32_e32 v240, v78, v238
	v_fmac_f32_e32 v223, v79, v239
	v_cvt_pk_bf16_f32 v219, v240, v223
	v_lshl_add_u64 v[236:237], v[236:237], 0, s[44:45]
	global_store_dwordx4 v[236:237], v[216:219], off offset:3072
	v_lshl_add_u64 v[232:233], v[232:233], 0, s[10:11]
	v_lshl_add_u64 v[234:235], v[234:235], 0, s[44:45]
	global_load_dwordx4 v[216:219], v[232:233], off
	global_load_dwordx4 v[220:223], v[234:235], off offset:3072
	s_waitcnt vmcnt(9)
	v_lshlrev_b32_e32 v238, 16, v224
	v_and_b32_e32 v239, s48, v224
	v_lshlrev_b32_e32 v240, 16, v228
	v_and_b32_e32 v228, s48, v228
	v_fmac_f32_e32 v240, v72, v238
	v_fmac_f32_e32 v228, v73, v239
	v_cvt_pk_bf16_f32 v224, v240, v228
	v_lshlrev_b32_e32 v238, 16, v225
	v_and_b32_e32 v239, s48, v225
	v_lshlrev_b32_e32 v240, 16, v229
	v_and_b32_e32 v229, s48, v229
	v_fmac_f32_e32 v240, v74, v238
	v_fmac_f32_e32 v229, v75, v239
	v_cvt_pk_bf16_f32 v225, v240, v229
	v_lshlrev_b32_e32 v238, 16, v226
	v_and_b32_e32 v239, s48, v226
	v_lshlrev_b32_e32 v240, 16, v230
	v_and_b32_e32 v230, s48, v230
	v_fmac_f32_e32 v240, v68, v238
	v_fmac_f32_e32 v230, v69, v239
	v_cvt_pk_bf16_f32 v226, v240, v230
	v_lshlrev_b32_e32 v238, 16, v227
	v_and_b32_e32 v239, s48, v227
	v_lshlrev_b32_e32 v240, 16, v231
	v_and_b32_e32 v231, s48, v231
	v_fmac_f32_e32 v240, v70, v238
	v_fmac_f32_e32 v231, v71, v239
	v_cvt_pk_bf16_f32 v227, v240, v231
	global_store_dwordx4 v[236:237], v[224:227], off offset:3328
	global_load_dwordx4 v[224:227], v[232:233], off offset:256
	global_load_dwordx4 v[228:231], v[234:235], off offset:3328
	s_waitcnt vmcnt(9)
	v_lshlrev_b32_e32 v238, 16, v200
	v_and_b32_e32 v239, s48, v200
	v_lshlrev_b32_e32 v240, 16, v204
	v_and_b32_e32 v204, s48, v204
	v_fmac_f32_e32 v240, v64, v238
	v_fmac_f32_e32 v204, v65, v239
	v_cvt_pk_bf16_f32 v200, v240, v204
	v_lshlrev_b32_e32 v238, 16, v201
	v_and_b32_e32 v239, s48, v201
	v_lshlrev_b32_e32 v240, 16, v205
	v_and_b32_e32 v205, s48, v205
	v_fmac_f32_e32 v240, v66, v238
	v_fmac_f32_e32 v205, v67, v239
	v_cvt_pk_bf16_f32 v201, v240, v205
	v_lshlrev_b32_e32 v238, 16, v202
	v_and_b32_e32 v239, s48, v202
	v_lshlrev_b32_e32 v240, 16, v206
	v_and_b32_e32 v206, s48, v206
	v_fmac_f32_e32 v240, v60, v238
	v_fmac_f32_e32 v206, v61, v239
	v_cvt_pk_bf16_f32 v202, v240, v206
	v_lshlrev_b32_e32 v238, 16, v203
	v_and_b32_e32 v239, s48, v203
	v_lshlrev_b32_e32 v240, 16, v207
	v_and_b32_e32 v207, s48, v207
	v_fmac_f32_e32 v240, v62, v238
	v_fmac_f32_e32 v207, v63, v239
	v_cvt_pk_bf16_f32 v203, v240, v207
	v_lshl_add_u64 v[236:237], v[236:237], 0, s[46:47]
	global_store_dwordx4 v[236:237], v[200:203], off offset:3072
	v_lshl_add_u64 v[232:233], v[232:233], 0, s[10:11]
	v_lshl_add_u64 v[234:235], v[234:235], 0, s[44:45]
	global_load_dwordx4 v[200:203], v[232:233], off
	global_load_dwordx4 v[204:207], v[234:235], off offset:3072
	s_waitcnt vmcnt(9)
	v_lshlrev_b32_e32 v238, 16, v208
	v_and_b32_e32 v239, s48, v208
	v_lshlrev_b32_e32 v240, 16, v212
	v_and_b32_e32 v212, s48, v212
	v_fmac_f32_e32 v240, v56, v238
	v_fmac_f32_e32 v212, v57, v239
	v_cvt_pk_bf16_f32 v208, v240, v212
	v_lshlrev_b32_e32 v238, 16, v209
	v_and_b32_e32 v239, s48, v209
	v_lshlrev_b32_e32 v240, 16, v213
	v_and_b32_e32 v213, s48, v213
	v_fmac_f32_e32 v240, v58, v238
	v_fmac_f32_e32 v213, v59, v239
	v_cvt_pk_bf16_f32 v209, v240, v213
	v_lshlrev_b32_e32 v238, 16, v210
	v_and_b32_e32 v239, s48, v210
	v_lshlrev_b32_e32 v240, 16, v214
	v_and_b32_e32 v214, s48, v214
	v_fmac_f32_e32 v240, v52, v238
	v_fmac_f32_e32 v214, v53, v239
	v_cvt_pk_bf16_f32 v210, v240, v214
	v_lshlrev_b32_e32 v238, 16, v211
	v_and_b32_e32 v239, s48, v211
	v_lshlrev_b32_e32 v240, 16, v215
	v_and_b32_e32 v215, s48, v215
	v_fmac_f32_e32 v240, v54, v238
	v_fmac_f32_e32 v215, v55, v239
	v_cvt_pk_bf16_f32 v211, v240, v215
	global_store_dwordx4 v[236:237], v[208:211], off offset:3328
	global_load_dwordx4 v[208:211], v[232:233], off offset:256
	global_load_dwordx4 v[212:215], v[234:235], off offset:3328
	s_waitcnt vmcnt(9)
	v_lshlrev_b32_e32 v238, 16, v216
	v_and_b32_e32 v239, s48, v216
	v_lshlrev_b32_e32 v240, 16, v220
	v_and_b32_e32 v220, s48, v220
	v_fmac_f32_e32 v240, v48, v238
	v_fmac_f32_e32 v220, v49, v239
	v_cvt_pk_bf16_f32 v216, v240, v220
	v_lshlrev_b32_e32 v238, 16, v217
	v_and_b32_e32 v239, s48, v217
	v_lshlrev_b32_e32 v240, 16, v221
	v_and_b32_e32 v221, s48, v221
	v_fmac_f32_e32 v240, v50, v238
	v_fmac_f32_e32 v221, v51, v239
	v_cvt_pk_bf16_f32 v217, v240, v221
	v_lshlrev_b32_e32 v238, 16, v218
	v_and_b32_e32 v239, s48, v218
	v_lshlrev_b32_e32 v240, 16, v222
	v_and_b32_e32 v222, s48, v222
	v_fmac_f32_e32 v240, v44, v238
	v_fmac_f32_e32 v222, v45, v239
	v_cvt_pk_bf16_f32 v218, v240, v222
	v_lshlrev_b32_e32 v238, 16, v219
	v_and_b32_e32 v239, s48, v219
	v_lshlrev_b32_e32 v240, 16, v223
	v_and_b32_e32 v223, s48, v223
	v_fmac_f32_e32 v240, v46, v238
	v_fmac_f32_e32 v223, v47, v239
	v_cvt_pk_bf16_f32 v219, v240, v223
	v_lshl_add_u64 v[236:237], v[236:237], 0, s[44:45]
	global_store_dwordx4 v[236:237], v[216:219], off offset:3072
	v_lshl_add_u64 v[232:233], v[232:233], 0, s[10:11]
	v_lshl_add_u64 v[234:235], v[234:235], 0, s[44:45]
	global_load_dwordx4 v[216:219], v[232:233], off
	global_load_dwordx4 v[220:223], v[234:235], off offset:3072
	s_waitcnt vmcnt(9)
	v_lshlrev_b32_e32 v238, 16, v224
	v_and_b32_e32 v239, s48, v224
	v_lshlrev_b32_e32 v240, 16, v228
	v_and_b32_e32 v228, s48, v228
	v_fmac_f32_e32 v240, v40, v238
	v_fmac_f32_e32 v228, v41, v239
	v_cvt_pk_bf16_f32 v224, v240, v228
	v_lshlrev_b32_e32 v238, 16, v225
	v_and_b32_e32 v239, s48, v225
	v_lshlrev_b32_e32 v240, 16, v229
	v_and_b32_e32 v229, s48, v229
	v_fmac_f32_e32 v240, v42, v238
	v_fmac_f32_e32 v229, v43, v239
	v_cvt_pk_bf16_f32 v225, v240, v229
	v_lshlrev_b32_e32 v238, 16, v226
	v_and_b32_e32 v239, s48, v226
	v_lshlrev_b32_e32 v240, 16, v230
	v_and_b32_e32 v230, s48, v230
	v_fmac_f32_e32 v240, v36, v238
	v_fmac_f32_e32 v230, v37, v239
	v_cvt_pk_bf16_f32 v226, v240, v230
	v_lshlrev_b32_e32 v238, 16, v227
	v_and_b32_e32 v239, s48, v227
	v_lshlrev_b32_e32 v240, 16, v231
	v_and_b32_e32 v231, s48, v231
	v_fmac_f32_e32 v240, v38, v238
	v_fmac_f32_e32 v231, v39, v239
	v_cvt_pk_bf16_f32 v227, v240, v231
	global_store_dwordx4 v[236:237], v[224:227], off offset:3328
	global_load_dwordx4 v[224:227], v[232:233], off offset:256
	global_load_dwordx4 v[228:231], v[234:235], off offset:3328
	s_waitcnt vmcnt(9)
	v_lshlrev_b32_e32 v238, 16, v200
	v_and_b32_e32 v239, s48, v200
	v_lshlrev_b32_e32 v240, 16, v204
	v_and_b32_e32 v204, s48, v204
	v_fmac_f32_e32 v240, v32, v238
	v_fmac_f32_e32 v204, v33, v239
	v_cvt_pk_bf16_f32 v200, v240, v204
	v_lshlrev_b32_e32 v238, 16, v201
	v_and_b32_e32 v239, s48, v201
	v_lshlrev_b32_e32 v240, 16, v205
	v_and_b32_e32 v205, s48, v205
	v_fmac_f32_e32 v240, v34, v238
	v_fmac_f32_e32 v205, v35, v239
	v_cvt_pk_bf16_f32 v201, v240, v205
	v_lshlrev_b32_e32 v238, 16, v202
	v_and_b32_e32 v239, s48, v202
	v_lshlrev_b32_e32 v240, 16, v206
	v_and_b32_e32 v206, s48, v206
	v_fmac_f32_e32 v240, v24, v238
	v_fmac_f32_e32 v206, v25, v239
	v_cvt_pk_bf16_f32 v202, v240, v206
	v_lshlrev_b32_e32 v238, 16, v203
	v_and_b32_e32 v239, s48, v203
	v_lshlrev_b32_e32 v240, 16, v207
	v_and_b32_e32 v207, s48, v207
	v_fmac_f32_e32 v240, v26, v238
	v_fmac_f32_e32 v207, v27, v239
	v_cvt_pk_bf16_f32 v203, v240, v207
	v_lshl_add_u64 v[236:237], v[236:237], 0, s[44:45]
	global_store_dwordx4 v[236:237], v[200:203], off offset:3072
	s_waitcnt vmcnt(7)
	v_lshlrev_b32_e32 v238, 16, v208
	v_and_b32_e32 v239, s48, v208
	v_lshlrev_b32_e32 v240, 16, v212
	v_and_b32_e32 v212, s48, v212
	v_fmac_f32_e32 v240, v20, v238
	v_fmac_f32_e32 v212, v21, v239
	v_cvt_pk_bf16_f32 v208, v240, v212
	v_lshlrev_b32_e32 v238, 16, v209
	v_and_b32_e32 v239, s48, v209
	v_lshlrev_b32_e32 v240, 16, v213
	v_and_b32_e32 v213, s48, v213
	v_fmac_f32_e32 v240, v22, v238
	v_fmac_f32_e32 v213, v23, v239
	v_cvt_pk_bf16_f32 v209, v240, v213
	v_lshlrev_b32_e32 v238, 16, v210
	v_and_b32_e32 v239, s48, v210
	v_lshlrev_b32_e32 v240, 16, v214
	v_and_b32_e32 v214, s48, v214
	v_fmac_f32_e32 v240, v16, v238
	v_fmac_f32_e32 v214, v17, v239
	v_cvt_pk_bf16_f32 v210, v240, v214
	v_lshlrev_b32_e32 v238, 16, v211
	v_and_b32_e32 v239, s48, v211
	v_lshlrev_b32_e32 v240, 16, v215
	v_and_b32_e32 v215, s48, v215
	v_fmac_f32_e32 v240, v18, v238
	v_fmac_f32_e32 v215, v19, v239
	v_cvt_pk_bf16_f32 v211, v240, v215
	global_store_dwordx4 v[236:237], v[208:211], off offset:3328
	s_waitcnt vmcnt(5)
	v_lshlrev_b32_e32 v238, 16, v216
	v_and_b32_e32 v239, s48, v216
	v_lshlrev_b32_e32 v240, 16, v220
	v_and_b32_e32 v220, s48, v220
	v_fmac_f32_e32 v240, v12, v238
	v_fmac_f32_e32 v220, v13, v239
	v_cvt_pk_bf16_f32 v216, v240, v220
	v_lshlrev_b32_e32 v238, 16, v217
	v_and_b32_e32 v239, s48, v217
	v_lshlrev_b32_e32 v240, 16, v221
	v_and_b32_e32 v221, s48, v221
	v_fmac_f32_e32 v240, v14, v238
	v_fmac_f32_e32 v221, v15, v239
	v_cvt_pk_bf16_f32 v217, v240, v221
	v_lshlrev_b32_e32 v238, 16, v218
	v_and_b32_e32 v239, s48, v218
	v_lshlrev_b32_e32 v240, 16, v222
	v_and_b32_e32 v222, s48, v222
	v_fmac_f32_e32 v240, v8, v238
	v_fmac_f32_e32 v222, v9, v239
	v_cvt_pk_bf16_f32 v218, v240, v222
	v_lshlrev_b32_e32 v238, 16, v219
	v_and_b32_e32 v239, s48, v219
	v_lshlrev_b32_e32 v240, 16, v223
	v_and_b32_e32 v223, s48, v223
	v_fmac_f32_e32 v240, v10, v238
	v_fmac_f32_e32 v223, v11, v239
	v_cvt_pk_bf16_f32 v219, v240, v223
	v_lshl_add_u64 v[236:237], v[236:237], 0, s[44:45]
	global_store_dwordx4 v[236:237], v[216:219], off offset:3072
	s_waitcnt vmcnt(3)
	v_lshlrev_b32_e32 v238, 16, v224
	v_and_b32_e32 v239, s48, v224
	v_lshlrev_b32_e32 v240, 16, v228
	v_and_b32_e32 v228, s48, v228
	v_fmac_f32_e32 v240, v4, v238
	v_fmac_f32_e32 v228, v5, v239
	v_cvt_pk_bf16_f32 v224, v240, v228
	v_lshlrev_b32_e32 v238, 16, v225
	v_and_b32_e32 v239, s48, v225
	v_lshlrev_b32_e32 v240, 16, v229
	v_and_b32_e32 v229, s48, v229
	v_fmac_f32_e32 v240, v6, v238
	v_fmac_f32_e32 v229, v7, v239
	v_cvt_pk_bf16_f32 v225, v240, v229
	v_lshlrev_b32_e32 v238, 16, v226
	v_and_b32_e32 v239, s48, v226
	v_lshlrev_b32_e32 v240, 16, v230
	v_and_b32_e32 v230, s48, v230
	v_fmac_f32_e32 v240, v0, v238
	v_fmac_f32_e32 v230, v1, v239
	v_cvt_pk_bf16_f32 v226, v240, v230
	v_lshlrev_b32_e32 v238, 16, v227
	v_and_b32_e32 v239, s48, v227
	v_lshlrev_b32_e32 v240, 16, v231
	v_and_b32_e32 v231, s48, v231
	v_fmac_f32_e32 v240, v2, v238
	v_fmac_f32_e32 v231, v3, v239
	v_cvt_pk_bf16_f32 v227, v240, v231
	global_store_dwordx4 v[236:237], v[224:227], off offset:3328
	s_branch .Lmrg_done
.Lmrg_first:
	global_load_dwordx4 v[200:203], v[232:233], off
	global_load_dwordx4 v[208:211], v[232:233], off offset:256
	v_lshl_add_u64 v[232:233], v[232:233], 0, s[10:11]
	global_load_dwordx4 v[216:219], v[232:233], off
	global_load_dwordx4 v[224:227], v[232:233], off offset:256
	s_waitcnt vmcnt(3)
	v_lshlrev_b32_e32 v238, 16, v200
	v_and_b32_e32 v239, s48, v200
	v_mul_f32_e32 v238, v128, v238
	v_mul_f32_e32 v239, v129, v239
	v_cvt_pk_bf16_f32 v200, v238, v239
	v_lshlrev_b32_e32 v238, 16, v201
	v_and_b32_e32 v239, s48, v201
	v_mul_f32_e32 v238, v130, v238
	v_mul_f32_e32 v239, v131, v239
	v_cvt_pk_bf16_f32 v201, v238, v239
	v_lshlrev_b32_e32 v238, 16, v202
	v_and_b32_e32 v239, s48, v202
	v_mul_f32_e32 v238, v124, v238
	v_mul_f32_e32 v239, v125, v239
	v_cvt_pk_bf16_f32 v202, v238, v239
	v_lshlrev_b32_e32 v238, 16, v203
	v_and_b32_e32 v239, s48, v203
	v_mul_f32_e32 v238, v126, v238
	v_mul_f32_e32 v239, v127, v239
	v_cvt_pk_bf16_f32 v203, v238, v239
	global_store_dwordx4 v[236:237], v[200:203], off offset:3072
	v_lshl_add_u64 v[232:233], v[232:233], 0, s[10:11]
	global_load_dwordx4 v[200:203], v[232:233], off
	s_waitcnt vmcnt(4)
	v_lshlrev_b32_e32 v238, 16, v208
	v_and_b32_e32 v239, s48, v208
	v_mul_f32_e32 v238, v120, v238
	v_mul_f32_e32 v239, v121, v239
	v_cvt_pk_bf16_f32 v208, v238, v239
	v_lshlrev_b32_e32 v238, 16, v209
	v_and_b32_e32 v239, s48, v209
	v_mul_f32_e32 v238, v122, v238
	v_mul_f32_e32 v239, v123, v239
	v_cvt_pk_bf16_f32 v209, v238, v239
	v_lshlrev_b32_e32 v238, 16, v210
	v_and_b32_e32 v239, s48, v210
	v_mul_f32_e32 v238, v116, v238
	v_mul_f32_e32 v239, v117, v239
	v_cvt_pk_bf16_f32 v210, v238, v239
	v_lshlrev_b32_e32 v238, 16, v211
	v_and_b32_e32 v239, s48, v211
	v_mul_f32_e32 v238, v118, v238
	v_mul_f32_e32 v239, v119, v239
	v_cvt_pk_bf16_f32 v211, v238, v239
	global_store_dwordx4 v[236:237], v[208:211], off offset:3328
	global_load_dwordx4 v[208:211], v[232:233], off offset:256
	s_waitcnt vmcnt(5)
	v_lshlrev_b32_e32 v238, 16, v216
	v_and_b32_e32 v239, s48, v216
	v_mul_f32_e32 v238, v112, v238
	v_mul_f32_e32 v239, v113, v239
	v_cvt_pk_bf16_f32 v216, v238, v239
	v_lshlrev_b32_e32 v238, 16, v217
	v_and_b32_e32 v239, s48, v217
	v_mul_f32_e32 v238, v114, v238
	v_mul_f32_e32 v239, v115, v239
	v_cvt_pk_bf16_f32 v217, v238, v239
	v_lshlrev_b32_e32 v238, 16, v218
	v_and_b32_e32 v239, s48, v218
	v_mul_f32_e32 v238, v108, v238
	v_mul_f32_e32 v239, v109, v239
	v_cvt_pk_bf16_f32 v218, v238, v239
	v_lshlrev_b32_e32 v238, 16, v219
	v_and_b32_e32 v239, s48, v219
	v_mul_f32_e32 v238, v110, v238
	v_mul_f32_e32 v239, v111, v239
	v_cvt_pk_bf16_f32 v219, v238, v239
	v_lshl_add_u64 v[236:237], v[236:237], 0, s[44:45]
	global_store_dwordx4 v[236:237], v[216:219], off offset:3072
	v_lshl_add_u64 v[232:233], v[232:233], 0, s[10:11]
	global_load_dwordx4 v[216:219], v[232:233], off
	s_waitcnt vmcnt(6)
	v_lshlrev_b32_e32 v238, 16, v224
	v_and_b32_e32 v239, s48, v224
	v_mul_f32_e32 v238, v104, v238
	v_mul_f32_e32 v239, v105, v239
	v_cvt_pk_bf16_f32 v224, v238, v239
	v_lshlrev_b32_e32 v238, 16, v225
	v_and_b32_e32 v239, s48, v225
	v_mul_f32_e32 v238, v106, v238
	v_mul_f32_e32 v239, v107, v239
	v_cvt_pk_bf16_f32 v225, v238, v239
	v_lshlrev_b32_e32 v238, 16, v226
	v_and_b32_e32 v239, s48, v226
	v_mul_f32_e32 v238, v100, v238
	v_mul_f32_e32 v239, v101, v239
	v_cvt_pk_bf16_f32 v226, v238, v239
	v_lshlrev_b32_e32 v238, 16, v227
	v_and_b32_e32 v239, s48, v227
	v_mul_f32_e32 v238, v102, v238
	v_mul_f32_e32 v239, v103, v239
	v_cvt_pk_bf16_f32 v227, v238, v239
	global_store_dwordx4 v[236:237], v[224:227], off offset:3328
	global_load_dwordx4 v[224:227], v[232:233], off offset:256
	s_waitcnt vmcnt(6)
	v_lshlrev_b32_e32 v238, 16, v200
	v_and_b32_e32 v239, s48, v200
	v_mul_f32_e32 v238, v96, v238
	v_mul_f32_e32 v239, v97, v239
	v_cvt_pk_bf16_f32 v200, v238, v239
	v_lshlrev_b32_e32 v238, 16, v201
	v_and_b32_e32 v239, s48, v201
	v_mul_f32_e32 v238, v98, v238
	v_mul_f32_e32 v239, v99, v239
	v_cvt_pk_bf16_f32 v201, v238, v239
	v_lshlrev_b32_e32 v238, 16, v202
	v_and_b32_e32 v239, s48, v202
	v_mul_f32_e32 v238, v92, v238
	v_mul_f32_e32 v239, v93, v239
	v_cvt_pk_bf16_f32 v202, v238, v239
	v_lshlrev_b32_e32 v238, 16, v203
	v_and_b32_e32 v239, s48, v203
	v_mul_f32_e32 v238, v94, v238
	v_mul_f32_e32 v239, v95, v239
	v_cvt_pk_bf16_f32 v203, v238, v239
	v_lshl_add_u64 v[236:237], v[236:237], 0, s[44:45]
	global_store_dwordx4 v[236:237], v[200:203], off offset:3072
	v_lshl_add_u64 v[232:233], v[232:233], 0, s[2:3]
	global_load_dwordx4 v[200:203], v[232:233], off
	s_waitcnt vmcnt(6)
	v_lshlrev_b32_e32 v238, 16, v208
	v_and_b32_e32 v239, s48, v208
	v_mul_f32_e32 v238, v88, v238
	v_mul_f32_e32 v239, v89, v239
	v_cvt_pk_bf16_f32 v208, v238, v239
	v_lshlrev_b32_e32 v238, 16, v209
	v_and_b32_e32 v239, s48, v209
	v_mul_f32_e32 v238, v90, v238
	v_mul_f32_e32 v239, v91, v239
	v_cvt_pk_bf16_f32 v209, v238, v239
	v_lshlrev_b32_e32 v238, 16, v210
	v_and_b32_e32 v239, s48, v210
	v_mul_f32_e32 v238, v84, v238
	v_mul_f32_e32 v239, v85, v239
	v_cvt_pk_bf16_f32 v210, v238, v239
	v_lshlrev_b32_e32 v238, 16, v211
	v_and_b32_e32 v239, s48, v211
	v_mul_f32_e32 v238, v86, v238
	v_mul_f32_e32 v239, v87, v239
	v_cvt_pk_bf16_f32 v211, v238, v239
	global_store_dwordx4 v[236:237], v[208:211], off offset:3328
	global_load_dwordx4 v[208:211], v[232:233], off offset:256
	s_waitcnt vmcnt(6)
	v_lshlrev_b32_e32 v238, 16, v216
	v_and_b32_e32 v239, s48, v216
	v_mul_f32_e32 v238, v80, v238
	v_mul_f32_e32 v239, v81, v239
	v_cvt_pk_bf16_f32 v216, v238, v239
	v_lshlrev_b32_e32 v238, 16, v217
	v_and_b32_e32 v239, s48, v217
	v_mul_f32_e32 v238, v82, v238
	v_mul_f32_e32 v239, v83, v239
	v_cvt_pk_bf16_f32 v217, v238, v239
	v_lshlrev_b32_e32 v238, 16, v218
	v_and_b32_e32 v239, s48, v218
	v_mul_f32_e32 v238, v76, v238
	v_mul_f32_e32 v239, v77, v239
	v_cvt_pk_bf16_f32 v218, v238, v239
	v_lshlrev_b32_e32 v238, 16, v219
	v_and_b32_e32 v239, s48, v219
	v_mul_f32_e32 v238, v78, v238
	v_mul_f32_e32 v239, v79, v239
	v_cvt_pk_bf16_f32 v219, v238, v239
	v_lshl_add_u64 v[236:237], v[236:237], 0, s[44:45]
	global_store_dwordx4 v[236:237], v[216:219], off offset:3072
	v_lshl_add_u64 v[232:233], v[232:233], 0, s[10:11]
	global_load_dwordx4 v[216:219], v[232:233], off
	s_waitcnt vmcnt(6)
	v_lshlrev_b32_e32 v238, 16, v224
	v_and_b32_e32 v239, s48, v224
	v_mul_f32_e32 v238, v72, v238
	v_mul_f32_e32 v239, v73, v239
	v_cvt_pk_bf16_f32 v224, v238, v239
	v_lshlrev_b32_e32 v238, 16, v225
	v_and_b32_e32 v239, s48, v225
	v_mul_f32_e32 v238, v74, v238
	v_mul_f32_e32 v239, v75, v239
	v_cvt_pk_bf16_f32 v225, v238, v239
	v_lshlrev_b32_e32 v238, 16, v226
	v_and_b32_e32 v239, s48, v226
	v_mul_f32_e32 v238, v68, v238
	v_mul_f32_e32 v239, v69, v239
	v_cvt_pk_bf16_f32 v226, v238, v239
	v_lshlrev_b32_e32 v238, 16, v227
	v_and_b32_e32 v239, s48, v227
	v_mul_f32_e32 v238, v70, v238
	v_mul_f32_e32 v239, v71, v239
	v_cvt_pk_bf16_f32 v227, v238, v239
	global_store_dwordx4 v[236:237], v[224:227], off offset:3328
	global_load_dwordx4 v[224:227], v[232:233], off offset:256
	s_waitcnt vmcnt(6)
	v_lshlrev_b32_e32 v238, 16, v200
	v_and_b32_e32 v239, s48, v200
	v_mul_f32_e32 v238, v64, v238
	v_mul_f32_e32 v239, v65, v239
	v_cvt_pk_bf16_f32 v200, v238, v239
	v_lshlrev_b32_e32 v238, 16, v201
	v_and_b32_e32 v239, s48, v201
	v_mul_f32_e32 v238, v66, v238
	v_mul_f32_e32 v239, v67, v239
	v_cvt_pk_bf16_f32 v201, v238, v239
	v_lshlrev_b32_e32 v238, 16, v202
	v_and_b32_e32 v239, s48, v202
	v_mul_f32_e32 v238, v60, v238
	v_mul_f32_e32 v239, v61, v239
	v_cvt_pk_bf16_f32 v202, v238, v239
	v_lshlrev_b32_e32 v238, 16, v203
	v_and_b32_e32 v239, s48, v203
	v_mul_f32_e32 v238, v62, v238
	v_mul_f32_e32 v239, v63, v239
	v_cvt_pk_bf16_f32 v203, v238, v239
	v_lshl_add_u64 v[236:237], v[236:237], 0, s[46:47]
	global_store_dwordx4 v[236:237], v[200:203], off offset:3072
	v_lshl_add_u64 v[232:233], v[232:233], 0, s[10:11]
	global_load_dwordx4 v[200:203], v[232:233], off
	s_waitcnt vmcnt(6)
	v_lshlrev_b32_e32 v238, 16, v208
	v_and_b32_e32 v239, s48, v208
	v_mul_f32_e32 v238, v56, v238
	v_mul_f32_e32 v239, v57, v239
	v_cvt_pk_bf16_f32 v208, v238, v239
	v_lshlrev_b32_e32 v238, 16, v209
	v_and_b32_e32 v239, s48, v209
	v_mul_f32_e32 v238, v58, v238
	v_mul_f32_e32 v239, v59, v239
	v_cvt_pk_bf16_f32 v209, v238, v239
	v_lshlrev_b32_e32 v238, 16, v210
	v_and_b32_e32 v239, s48, v210
	v_mul_f32_e32 v238, v52, v238
	v_mul_f32_e32 v239, v53, v239
	v_cvt_pk_bf16_f32 v210, v238, v239
	v_lshlrev_b32_e32 v238, 16, v211
	v_and_b32_e32 v239, s48, v211
	v_mul_f32_e32 v238, v54, v238
	v_mul_f32_e32 v239, v55, v239
	v_cvt_pk_bf16_f32 v211, v238, v239
	global_store_dwordx4 v[236:237], v[208:211], off offset:3328
	global_load_dwordx4 v[208:211], v[232:233], off offset:256
	s_waitcnt vmcnt(6)
	v_lshlrev_b32_e32 v238, 16, v216
	v_and_b32_e32 v239, s48, v216
	v_mul_f32_e32 v238, v48, v238
	v_mul_f32_e32 v239, v49, v239
	v_cvt_pk_bf16_f32 v216, v238, v239
	v_lshlrev_b32_e32 v238, 16, v217
	v_and_b32_e32 v239, s48, v217
	v_mul_f32_e32 v238, v50, v238
	v_mul_f32_e32 v239, v51, v239
	v_cvt_pk_bf16_f32 v217, v238, v239
	v_lshlrev_b32_e32 v238, 16, v218
	v_and_b32_e32 v239, s48, v218
	v_mul_f32_e32 v238, v44, v238
	v_mul_f32_e32 v239, v45, v239
	v_cvt_pk_bf16_f32 v218, v238, v239
	v_lshlrev_b32_e32 v238, 16, v219
	v_and_b32_e32 v239, s48, v219
	v_mul_f32_e32 v238, v46, v238
	v_mul_f32_e32 v239, v47, v239
	v_cvt_pk_bf16_f32 v219, v238, v239
	v_lshl_add_u64 v[236:237], v[236:237], 0, s[44:45]
	global_store_dwordx4 v[236:237], v[216:219], off offset:3072
	v_lshl_add_u64 v[232:233], v[232:233], 0, s[10:11]
	global_load_dwordx4 v[216:219], v[232:233], off
	s_waitcnt vmcnt(6)
	v_lshlrev_b32_e32 v238, 16, v224
	v_and_b32_e32 v239, s48, v224
	v_mul_f32_e32 v238, v40, v238
	v_mul_f32_e32 v239, v41, v239
	v_cvt_pk_bf16_f32 v224, v238, v239
	v_lshlrev_b32_e32 v238, 16, v225
	v_and_b32_e32 v239, s48, v225
	v_mul_f32_e32 v238, v42, v238
	v_mul_f32_e32 v239, v43, v239
	v_cvt_pk_bf16_f32 v225, v238, v239
	v_lshlrev_b32_e32 v238, 16, v226
	v_and_b32_e32 v239, s48, v226
	v_mul_f32_e32 v238, v36, v238
	v_mul_f32_e32 v239, v37, v239
	v_cvt_pk_bf16_f32 v226, v238, v239
	v_lshlrev_b32_e32 v238, 16, v227
	v_and_b32_e32 v239, s48, v227
	v_mul_f32_e32 v238, v38, v238
	v_mul_f32_e32 v239, v39, v239
	v_cvt_pk_bf16_f32 v227, v238, v239
	global_store_dwordx4 v[236:237], v[224:227], off offset:3328
	global_load_dwordx4 v[224:227], v[232:233], off offset:256
	s_waitcnt vmcnt(6)
	v_lshlrev_b32_e32 v238, 16, v200
	v_and_b32_e32 v239, s48, v200
	v_mul_f32_e32 v238, v32, v238
	v_mul_f32_e32 v239, v33, v239
	v_cvt_pk_bf16_f32 v200, v238, v239
	v_lshlrev_b32_e32 v238, 16, v201
	v_and_b32_e32 v239, s48, v201
	v_mul_f32_e32 v238, v34, v238
	v_mul_f32_e32 v239, v35, v239
	v_cvt_pk_bf16_f32 v201, v238, v239
	v_lshlrev_b32_e32 v238, 16, v202
	v_and_b32_e32 v239, s48, v202
	v_mul_f32_e32 v238, v24, v238
	v_mul_f32_e32 v239, v25, v239
	v_cvt_pk_bf16_f32 v202, v238, v239
	v_lshlrev_b32_e32 v238, 16, v203
	v_and_b32_e32 v239, s48, v203
	v_mul_f32_e32 v238, v26, v238
	v_mul_f32_e32 v239, v27, v239
	v_cvt_pk_bf16_f32 v203, v238, v239
	v_lshl_add_u64 v[236:237], v[236:237], 0, s[44:45]
	global_store_dwordx4 v[236:237], v[200:203], off offset:3072
	s_waitcnt vmcnt(5)
	v_lshlrev_b32_e32 v238, 16, v208
	v_and_b32_e32 v239, s48, v208
	v_mul_f32_e32 v238, v20, v238
	v_mul_f32_e32 v239, v21, v239
	v_cvt_pk_bf16_f32 v208, v238, v239
	v_lshlrev_b32_e32 v238, 16, v209
	v_and_b32_e32 v239, s48, v209
	v_mul_f32_e32 v238, v22, v238
	v_mul_f32_e32 v239, v23, v239
	v_cvt_pk_bf16_f32 v209, v238, v239
	v_lshlrev_b32_e32 v238, 16, v210
	v_and_b32_e32 v239, s48, v210
	v_mul_f32_e32 v238, v16, v238
	v_mul_f32_e32 v239, v17, v239
	v_cvt_pk_bf16_f32 v210, v238, v239
	v_lshlrev_b32_e32 v238, 16, v211
	v_and_b32_e32 v239, s48, v211
	v_mul_f32_e32 v238, v18, v238
	v_mul_f32_e32 v239, v19, v239
	v_cvt_pk_bf16_f32 v211, v238, v239
	global_store_dwordx4 v[236:237], v[208:211], off offset:3328
	s_waitcnt vmcnt(4)
	v_lshlrev_b32_e32 v238, 16, v216
	v_and_b32_e32 v239, s48, v216
	v_mul_f32_e32 v238, v12, v238
	v_mul_f32_e32 v239, v13, v239
	v_cvt_pk_bf16_f32 v216, v238, v239
	v_lshlrev_b32_e32 v238, 16, v217
	v_and_b32_e32 v239, s48, v217
	v_mul_f32_e32 v238, v14, v238
	v_mul_f32_e32 v239, v15, v239
	v_cvt_pk_bf16_f32 v217, v238, v239
	v_lshlrev_b32_e32 v238, 16, v218
	v_and_b32_e32 v239, s48, v218
	v_mul_f32_e32 v238, v8, v238
	v_mul_f32_e32 v239, v9, v239
	v_cvt_pk_bf16_f32 v218, v238, v239
	v_lshlrev_b32_e32 v238, 16, v219
	v_and_b32_e32 v239, s48, v219
	v_mul_f32_e32 v238, v10, v238
	v_mul_f32_e32 v239, v11, v239
	v_cvt_pk_bf16_f32 v219, v238, v239
	v_lshl_add_u64 v[236:237], v[236:237], 0, s[44:45]
	global_store_dwordx4 v[236:237], v[216:219], off offset:3072
	s_waitcnt vmcnt(3)
	v_lshlrev_b32_e32 v238, 16, v224
	v_and_b32_e32 v239, s48, v224
	v_mul_f32_e32 v238, v4, v238
	v_mul_f32_e32 v239, v5, v239
	v_cvt_pk_bf16_f32 v224, v238, v239
	v_lshlrev_b32_e32 v238, 16, v225
	v_and_b32_e32 v239, s48, v225
	v_mul_f32_e32 v238, v6, v238
	v_mul_f32_e32 v239, v7, v239
	v_cvt_pk_bf16_f32 v225, v238, v239
	v_lshlrev_b32_e32 v238, 16, v226
	v_and_b32_e32 v239, s48, v226
	v_mul_f32_e32 v238, v0, v238
	v_mul_f32_e32 v239, v1, v239
	v_cvt_pk_bf16_f32 v226, v238, v239
	v_lshlrev_b32_e32 v238, 16, v227
	v_and_b32_e32 v239, s48, v227
	v_mul_f32_e32 v238, v2, v238
	v_mul_f32_e32 v239, v3, v239
	v_cvt_pk_bf16_f32 v227, v238, v239
	global_store_dwordx4 v[236:237], v[224:227], off offset:3328
.Lmrg_done:
	s_and_b64 vcc, exec, s[38:39]
	s_mov_b64 s[0:1], -1
	s_cbranch_vccnz .LBB0_432
	s_andn2_b64 vcc, exec, s[8:9]
	s_cbranch_vccnz .LBB0_431
	s_barrier
	s_branch .LBB0_431
